# on top of previous: RWKV-7 chunk forward substitution rewritten right-looking (f32 FMAs, M streamed from LDS two rows ahead); P2/P5 MFMA operand fragments all read before the MFMA chain with counted w
# speedup vs baseline: 1.0161x; 1.0073x over previous
; DI bf16_t f2bf(float f) { return (bf16_t)(pack2(f, 0.f) & 0xFFFFu); }
; #define MFMA32(a, b, c) __builtin_amdgcn_mfma_f32_32x32x16_bf16((a), (b), (c), 0, 0, 0)
; __device__ __forceinline__ void rwkv_chunked(unsigned char* smem, CP p, int L, int b, int h) {
;     ...
;         { float ev[16];
; #pragma unroll
;           for (int j = 0; j < 16; ++j) ev[j] = EW[j * 64 + c];
; #pragma unroll
;           for (int i = 0; i < 2; ++i) { const int t = wv * 2 + i; float cum = 0.f;
; #pragma unroll
;             for (int j = 0; j < 16; ++j) cum += (j <= t) ? ev[j] : 0.f;
;             const float Pt = __expf(-cum), Pm = __expf(-(cum - ew_[i])), iP = __expf(cum);
;             const float al = -nk_[i] * Pm, rh = r_[i] * Pt, be = ab_[i] * iP, ka = kx_[i] * iP;
;             AR[t * 72 + c] = f2bf(al); AR[(16 + t) * 72 + c] = f2bf(rh); BKr[t * 72 + c] = f2bf(be); BKr[(16 + t) * 72 + c] = f2bf(ka);
;             BKt[c * 40 + t] = f2bf(be); BKt[c * 40 + 16 + t] = f2bf(ka);
;             UV[c * 40 + 16 + t] = f2bf(v_[i]); VS[t * 64 + c] = v_[i];
;             if (t == 15) PC[c] = Pt; } }
;     ...
;         } else if (wv < 3) {
;             const int vb = wv - 1;
; #pragma unroll
;             for (int s = 0; s < 4; ++s) acc = MFMA32(*(const bf16x8*)(ZB + (32 * vb + qi) * 72 + 16 * s + 8 * hl), *(const bf16x8*)(AR + qi * 72 + 16 * s + 8 * hl), acc);
;         }
.LBB0_669:
	v_add_f32_e32 v13, v13, v14
	v_max_f32_e32 v13, 0x179abe15, v13
	v_add_f32_e32 v14, v32, v33
	v_rsq_f32_e32 v13, v13
	v_max_f32_e32 v14, 0x179abe15, v14
	v_rsq_f32_e32 v14, v14
	v_lshlrev_b32_e32 v11, 16, v11
	v_lshlrev_b32_e32 v44, 16, v0
	v_lshlrev_b32_e32 v3, 16, v3
	v_sub_f32_e32 v0, v11, v44
	v_mul_f32_e32 v13, v10, v13
	v_sub_f32_e32 v10, v44, v3
	v_fmac_f32_e32 v44, v64, v0
	v_fmac_f32_e32 v3, v64, v10
	v_mul_f32_e32 v45, v15, v14
	ds_read2st64_b32 v[10:11], v76 offset0:106 offset1:107
	ds_read2st64_b32 v[14:15], v76 offset0:108 offset1:109
	ds_read2st64_b32 v[32:33], v76 offset0:110 offset1:111
	ds_read2st64_b32 v[34:35], v76 offset0:112 offset1:113
	ds_read2st64_b32 v[36:37], v76 offset0:114 offset1:115
	ds_read2st64_b32 v[38:39], v76 offset0:116 offset1:117
	ds_read2st64_b32 v[40:41], v76 offset0:118 offset1:119
	ds_read2st64_b32 v[42:43], v76 offset0:120 offset1:121
	s_waitcnt lgkmcnt(7)
	v_add_f32_e32 v0, 0, v10
	v_cndmask_b32_e64 v0, v0, 0, s[58:59]
	v_cndmask_b32_e64 v10, v11, 0, s[60:61]
	v_add_f32_e32 v10, v0, v10
	s_waitcnt lgkmcnt(6)
	v_cndmask_b32_e64 v46, v14, 0, s[60:61]
	v_add_f32_e32 v10, v10, v46
	v_cndmask_b32_e64 v46, v15, 0, s[62:63]
	v_add_f32_e32 v10, v10, v46
	s_waitcnt lgkmcnt(5)
	v_cndmask_b32_e64 v46, v32, 0, s[62:63]
	v_add_f32_e32 v10, v10, v46
	v_cndmask_b32_e64 v46, v33, 0, s[54:55]
	v_add_f32_e32 v10, v10, v46
	s_waitcnt lgkmcnt(4)
	v_cndmask_b32_e64 v46, v34, 0, s[54:55]
	v_add_f32_e32 v10, v10, v46
	v_cndmask_b32_e64 v46, v35, 0, s[64:65]
	v_add_f32_e32 v10, v10, v46
	s_waitcnt lgkmcnt(3)
	v_cndmask_b32_e64 v46, v36, 0, s[64:65]
	v_add_f32_e32 v10, v10, v46
	v_cndmask_b32_e64 v46, v37, 0, s[66:67]
	v_add_f32_e32 v10, v10, v46
	s_waitcnt lgkmcnt(2)
	v_cndmask_b32_e64 v46, v38, 0, s[66:67]
	v_add_f32_e32 v10, v10, v46
	v_cndmask_b32_e64 v46, v39, 0, s[68:69]
	v_add_f32_e32 v10, v10, v46
	s_waitcnt lgkmcnt(1)
	v_cndmask_b32_e64 v46, v40, 0, s[68:69]
	v_add_f32_e32 v10, v10, v46
	v_cndmask_b32_e64 v46, v41, 0, s[70:71]
	v_add_f32_e32 v10, v10, v46
	s_waitcnt lgkmcnt(0)
	v_cndmask_b32_e64 v46, v42, 0, s[70:71]
	v_add_f32_e32 v10, v10, v46
	v_cndmask_b32_e64 v46, v43, 0, s[72:73]
	v_add_f32_e32 v10, v10, v46
	v_mov_b32_e32 v114, v10
	v_sub_f32_e32 v5, v10, v5
	v_mul_f32_e32 v46, 0xbfb8aa3b, v10
	v_mul_f32_e32 v5, 0xbfb8aa3b, v5
	v_exp_f32_e32 v46, v46
	v_exp_f32_e32 v5, v5
	v_mul_f32_e32 v10, 0x3fb8aa3b, v10
	v_exp_f32_e32 v10, v10
	v_mul_f32_e32 v9, v9, v13
	v_mul_f32_e64 v5, v5, -v13
	v_mul_f32_e32 v4, v4, v46
	v_mul_f32_e32 v9, v9, v10
	v_mul_f32_e32 v7, v7, v10
	v_cvt_pk_bf16_f32 v5, v5, s0
	v_cvt_pk_bf16_f32 v4, v4, s0
	ds_write_b16 v92, v5 offset:9216
	ds_write_b16 v92, v4 offset:11520
	v_cvt_pk_bf16_f32 v4, v9, s0
	v_cvt_pk_bf16_f32 v5, v7, s0
	ds_write_b16 v92, v4 offset:31232
	ds_write_b16 v92, v5 offset:33536
	ds_write_b16 v94, v4 offset:13824
	ds_write_b16 v95, v5 offset:13856
	v_add_f32_e32 v5, v114, v6
	v_sub_f32_e32 v6, v5, v6
	v_mul_f32_e32 v0, 0xbfb8aa3b, v5
	v_mul_f32_e32 v6, 0xbfb8aa3b, v6
	v_exp_f32_e32 v0, v0
	v_exp_f32_e32 v6, v6
	v_mul_f32_e32 v5, 0x3fb8aa3b, v5
	v_exp_f32_e32 v5, v5
	v_cvt_pk_bf16_f32 v4, v44, s0
	ds_write_b16 v95, v4 offset:18976
	v_add_u32_e32 v4, v77, v90
	v_mul_f32_e32 v12, v12, v45
	ds_write_b32 v4, v44 offset:61312
	v_mul_f32_e64 v4, v6, -v45
	v_mul_f32_e32 v2, v2, v0
	v_mul_f32_e32 v6, v12, v5
	v_mul_f32_e32 v5, v8, v5
	v_cvt_pk_bf16_f32 v4, v4, s0
	v_cvt_pk_bf16_f32 v2, v2, s0
	ds_write_b16 v96, v4 offset:9216
	ds_write_b16 v96, v2 offset:11520
	v_cvt_pk_bf16_f32 v2, v6, s0
	v_cvt_pk_bf16_f32 v4, v5, s0
	ds_write_b16 v96, v2 offset:31232
	ds_write_b16 v96, v4 offset:33536
	ds_write_b16 v94, v2 offset:13826
	ds_write_b16 v97, v4 offset:13856
	v_cvt_pk_bf16_f32 v2, v3, s0
	ds_write_b16 v97, v2 offset:18976
	v_add_u32_e32 v2, v77, v98
	ds_write_b32 v2, v3 offset:61312
	s_and_saveexec_b64 s[16:17], s[8:9]
	ds_write_b32 v77, v0 offset:65408
	s_or_b64 exec, exec, s[16:17]
	s_waitcnt lgkmcnt(0)
	s_barrier
	s_and_saveexec_b64 s[16:17], s[48:49]
	s_xor_b64 vcc, exec, s[16:17]
	s_cbranch_execz .LBB0_675
	v_mov_b32_e32 v14, v1
	v_mov_b32_e32 v15, v1
	v_mov_b32_e32 v0, v1
	v_mov_b32_e32 v2, v1
	v_mov_b32_e32 v3, v1
	v_mov_b32_e32 v4, v1
	v_mov_b32_e32 v5, v1
	v_mov_b32_e32 v6, v1
	v_mov_b32_e32 v7, v1
	v_mov_b32_e32 v8, v1
	v_mov_b32_e32 v9, v1
	v_mov_b32_e32 v10, v1
	v_mov_b32_e32 v11, v1
	v_mov_b32_e32 v12, v1
	v_mov_b32_e32 v13, v1
	v_mov_b64_e32 v[46:47], v[14:15]
	v_mov_b64_e32 v[44:45], v[12:13]
	v_mov_b64_e32 v[42:43], v[10:11]
	v_mov_b64_e32 v[40:41], v[8:9]
	v_mov_b64_e32 v[38:39], v[6:7]
	v_mov_b64_e32 v[36:37], v[4:5]
	v_mov_b64_e32 v[34:35], v[2:3]
	v_mov_b64_e32 v[32:33], v[0:1]
	s_and_saveexec_b64 s[16:17], s[54:55]
	s_cbranch_execz .LBB0_674
	ds_read_b128 v[2:5], v79
	ds_read_b128 v[6:9], v80 offset:9216
	ds_read_b128 v[114:117], v79 offset:32
	ds_read_b128 v[118:121], v80 offset:9248
	ds_read_b128 v[122:125], v79 offset:64
	ds_read_b128 v[126:129], v80 offset:9280
	ds_read_b128 v[130:133], v79 offset:96
	ds_read_b128 v[134:137], v80 offset:9312
	s_waitcnt lgkmcnt(6)
	v_mfma_f32_32x32x16_bf16 v[32:47], v[2:5], v[6:9], 0
	s_waitcnt lgkmcnt(4)
	v_mfma_f32_32x32x16_bf16 v[32:47], v[114:117], v[118:121], v[32:47]
	s_waitcnt lgkmcnt(2)
	v_mfma_f32_32x32x16_bf16 v[32:47], v[122:125], v[126:129], v[32:47]
	s_waitcnt lgkmcnt(0)
	v_mfma_f32_32x32x16_bf16 v[32:47], v[130:133], v[134:137], v[32:47]

; DI bf16_t f2bf(float f) { return (bf16_t)(pack2(f, 0.f) & 0xFFFFu); }
; #define MFMA32(a, b, c) __builtin_amdgcn_mfma_f32_32x32x16_bf16((a), (b), (c), 0, 0, 0)
; DI int crow16(int i, int hl) { return (i & 3) + 8 * (i >> 2) + 4 * hl; }
; __device__ __forceinline__ void rwkv_chunked(unsigned char* smem, CP p, int L, int b, int h) {
;     ...
;         if (wv == 0) {
; #pragma unroll
;             for (int s = 0; s < 4; ++s) acc = MFMA32(*(const bf16x8*)(BKr + qi * 72 + 16 * s + 8 * hl), *(const bf16x8*)(AR + qi * 72 + 16 * s + 8 * hl), acc);
; #pragma unroll
;             for (int i = 0; i < 16; ++i) { const int j = crow16(i, hl), n = qi; const float m = acc[i];
;                 if (j < 16) { if (n < 16) Mf[j * 17 + n] = m; MT2[n * 24 + j] = f2bf((n >= 16 && j <= n - 16) ? m : 0.f); }
;                 else { const int i2 = j - 16; const bool k1 = n < 16 ? (i2 < n) : (i2 <= n - 16); MT1[n * 24 + i2] = f2bf(k1 ? m : 0.f); } }
.LBB0_675:
	s_andn2_saveexec_b64 vcc, vcc
	s_cbranch_execz .LBB0_693
	ds_read_b128 v[2:5], v80 offset:31232
	ds_read_b128 v[6:9], v80 offset:9216
	ds_read_b128 v[114:117], v80 offset:31264
	ds_read_b128 v[118:121], v80 offset:9248
	ds_read_b128 v[122:125], v80 offset:31296
	ds_read_b128 v[126:129], v80 offset:9280
	ds_read_b128 v[130:133], v80 offset:31328
	ds_read_b128 v[134:137], v80 offset:9312
	s_waitcnt lgkmcnt(6)
	v_mfma_f32_32x32x16_bf16 v[32:47], v[2:5], v[6:9], 0
	s_waitcnt lgkmcnt(4)
	v_mfma_f32_32x32x16_bf16 v[32:47], v[114:117], v[118:121], v[32:47]
	s_waitcnt lgkmcnt(2)
	v_mfma_f32_32x32x16_bf16 v[32:47], v[122:125], v[126:129], v[32:47]
	s_waitcnt lgkmcnt(0)
	v_mfma_f32_32x32x16_bf16 v[32:47], v[130:133], v[134:137], v[32:47]
	s_and_saveexec_b64 s[16:17], s[10:11]
	s_nop 10
	ds_write_b32 v102, v32 offset:48640
	s_or_b64 exec, exec, s[16:17]
	v_readlane_b32 s14, v255, 12
	v_cvt_pk_bf16_f32 v0, v32, s0
	v_readlane_b32 s15, v255, 13
	s_nop 1
	v_cndmask_b32_e64 v0, v0, 0, s[14:15]
	v_cndmask_b32_e64 v0, 0, v0, s[56:57]
	ds_write_b16 v99, v0 offset:25600
	s_and_saveexec_b64 s[16:17], s[10:11]
	ds_write_b32 v106, v33 offset:48640
	s_or_b64 exec, exec, s[16:17]
	v_readlane_b32 s14, v255, 14
	v_cvt_pk_bf16_f32 v0, v33, s0
	v_readlane_b32 s15, v255, 15
	s_nop 1
	v_cndmask_b32_e64 v0, 0, v0, s[14:15]
	ds_write_b16 v99, v0 offset:25602
	s_and_saveexec_b64 s[16:17], s[10:11]
	ds_write_b32 v106, v34 offset:48708
	s_or_b64 exec, exec, s[16:17]
	v_readlane_b32 s14, v255, 16
	v_cvt_pk_bf16_f32 v0, v34, s0
	v_readlane_b32 s15, v255, 17
	s_nop 1
	v_cndmask_b32_e64 v0, v0, 0, s[14:15]
	v_cndmask_b32_e64 v0, 0, v0, s[56:57]
	ds_write_b16 v99, v0 offset:25604
	s_and_saveexec_b64 s[16:17], s[10:11]
	ds_write_b32 v106, v35 offset:48776
	s_or_b64 exec, exec, s[16:17]
	v_readlane_b32 s14, v255, 18
	v_cvt_pk_bf16_f32 v0, v35, s0
	v_readlane_b32 s15, v255, 19
	s_nop 1
	v_cndmask_b32_e64 v0, v0, 0, s[14:15]
	v_cndmask_b32_e64 v0, 0, v0, s[56:57]
	ds_write_b16 v99, v0 offset:25606
	s_and_saveexec_b64 s[16:17], s[10:11]
	ds_write_b32 v106, v36 offset:49116
	s_or_b64 exec, exec, s[16:17]
	v_readlane_b32 s14, v255, 21
	v_cvt_pk_bf16_f32 v0, v36, s0
	v_readlane_b32 s15, v255, 22
	s_nop 1
	v_cndmask_b32_e64 v0, v0, 0, s[14:15]
	v_cndmask_b32_e64 v0, 0, v0, s[56:57]
	ds_write_b16 v99, v0 offset:25616
	s_and_saveexec_b64 s[16:17], s[10:11]
	ds_write_b32 v106, v37 offset:49184
	s_or_b64 exec, exec, s[16:17]
	v_readlane_b32 s14, v255, 23
	v_cvt_pk_bf16_f32 v0, v37, s0
	v_readlane_b32 s15, v255, 24
	s_nop 1
	v_cndmask_b32_e64 v0, v0, 0, s[14:15]
	v_cndmask_b32_e64 v0, 0, v0, s[56:57]
	ds_write_b16 v99, v0 offset:25618
	s_and_saveexec_b64 s[16:17], s[10:11]
	ds_write_b32 v106, v38 offset:49252
	s_or_b64 exec, exec, s[16:17]
	v_readlane_b32 s14, v255, 25
	v_cvt_pk_bf16_f32 v0, v38, s0
	v_readlane_b32 s15, v255, 26
	s_nop 1
	v_cndmask_b32_e64 v0, v0, 0, s[14:15]
	v_cndmask_b32_e64 v0, 0, v0, s[56:57]
	ds_write_b16 v99, v0 offset:25620
	s_and_saveexec_b64 s[16:17], s[10:11]
	ds_write_b32 v106, v39 offset:49320
	s_or_b64 exec, exec, s[16:17]
	v_readlane_b32 s14, v255, 27
	v_cvt_pk_bf16_f32 v0, v39, s0
	v_readlane_b32 s15, v255, 28
	v_cvt_pk_bf16_f32 v2, v41, s0
	v_cvt_pk_bf16_f32 v3, v42, s0
	v_cndmask_b32_e64 v0, v0, 0, s[14:15]
	v_cndmask_b32_e64 v0, 0, v0, s[56:57]
	ds_write_b16 v99, v0 offset:25622
	v_cvt_pk_bf16_f32 v0, v40, s0
	v_cvt_pk_bf16_f32 v4, v43, s0
	v_cndmask_b32_e64 v0, 0, v0, s[28:29]
	v_cndmask_b32_e64 v2, 0, v2, s[30:31]
	v_cndmask_b32_e64 v3, 0, v3, s[34:35]
	v_cndmask_b32_e64 v4, 0, v4, s[36:37]
	s_mov_b32 s14, 0x5040100
	v_perm_b32 v3, v4, v3, s14
	v_perm_b32 v2, v2, v0, s14
	v_cvt_pk_bf16_f32 v0, v44, s0
	v_cvt_pk_bf16_f32 v4, v45, s0
	v_cvt_pk_bf16_f32 v5, v46, s0
	v_cvt_pk_bf16_f32 v6, v47, s0
	v_cndmask_b32_e64 v0, 0, v0, s[38:39]
	v_cndmask_b32_e64 v4, 0, v4, s[42:43]
	v_cndmask_b32_e64 v5, 0, v5, s[40:41]
	v_cndmask_b32_e64 v6, 0, v6, s[0:1]
	v_perm_b32 v5, v6, v5, s14
	v_perm_b32 v4, v4, v0, s14
	v_add_u32_e32 v0, 0x5800, v99
	ds_write2_b64 v0, v[2:3], v[4:5] offset0:192 offset1:194

; DI bf16_t f2bf(float f) { return (bf16_t)(pack2(f, 0.f) & 0xFFFFu); }
; __device__ __forceinline__ void rwkv_chunked(unsigned char* smem, CP p, int L, int b, int h) {
;     ...
;         if (wv == 0) {
;             float u[16], cur[16], nxt[16], gcur, gnxt = 0.f;
; #pragma unroll
;             for (int i = 0; i < 16; ++i) { cur[i] = 0.f; nxt[i] = 0.f; }
;             gcur = Gs[lane * 17];
; #pragma unroll
;             for (int t = 0; t < 16; ++t) {
;                 if (t + 1 < 16) { gnxt = Gs[lane * 17 + t + 1];
; #pragma unroll
;                     for (int i = 0; i <= t; ++i) nxt[i] = Mf[i * 17 + t + 1]; }
;                 float x0 = gcur, x1 = 0.f;
; #pragma unroll
;                 for (int i = 0; i < t; ++i) { if (i & 1) x1 += u[i] * cur[i]; else x0 += u[i] * cur[i]; }
;                 u[t] = x0 + x1; UV[lane * 40 + t] = f2bf(u[t]);
; #pragma unroll
;                 for (int i = 0; i < 16; ++i) cur[i] = nxt[i];
;                 gcur = gnxt; }
;         }
.LBB0_697:
	s_or_b64 exec, exec, s[16:17]
	s_waitcnt lgkmcnt(0)
	s_barrier
	s_and_saveexec_b64 vcc, s[46:47]
	s_cbranch_execz .LBB0_699
	v_mov_b32_e32 v0, 0xbe00
	v_add_u32_e32 v154, 0xce80, v85
	ds_read2_b32 v[114:115], v154 offset0:0 offset1:1
	ds_read2_b32 v[116:117], v154 offset0:2 offset1:3
	ds_read2_b32 v[118:119], v154 offset0:4 offset1:5
	ds_read2_b32 v[120:121], v154 offset0:6 offset1:7
	ds_read2_b32 v[122:123], v154 offset0:8 offset1:9
	ds_read2_b32 v[124:125], v154 offset0:10 offset1:11
	ds_read2_b32 v[126:127], v154 offset0:12 offset1:13
	ds_read2_b32 v[128:129], v154 offset0:14 offset1:15
	ds_read2_b32 v[2:3], v0 offset0:1 offset1:2
	ds_read2_b32 v[4:5], v0 offset0:3 offset1:4
	ds_read2_b32 v[6:7], v0 offset0:5 offset1:6
	ds_read2_b32 v[8:9], v0 offset0:7 offset1:8
	ds_read2_b32 v[10:11], v0 offset0:9 offset1:10
	ds_read2_b32 v[12:13], v0 offset0:11 offset1:12
	ds_read2_b32 v[14:15], v0 offset0:13 offset1:14
	ds_read2_b32 v[130:131], v0 offset0:15 offset1:19
	ds_read2_b32 v[132:133], v0 offset0:20 offset1:21
	ds_read2_b32 v[134:135], v0 offset0:22 offset1:23
	ds_read2_b32 v[136:137], v0 offset0:24 offset1:25
	ds_read2_b32 v[138:139], v0 offset0:26 offset1:27
	ds_read2_b32 v[140:141], v0 offset0:28 offset1:29
	ds_read2_b32 v[142:143], v0 offset0:30 offset1:31
	ds_read2_b32 v[144:145], v0 offset0:32 offset1:37
	ds_read2_b32 v[146:147], v0 offset0:38 offset1:39
	ds_read2_b32 v[148:149], v0 offset0:40 offset1:41
	ds_read2_b32 v[150:151], v0 offset0:42 offset1:43
	ds_read2_b32 v[152:153], v0 offset0:44 offset1:45
	ds_read2_b32 v[156:157], v0 offset0:46 offset1:47
	ds_read2_b32 v[158:159], v0 offset0:48 offset1:49
	s_waitcnt lgkmcnt(13)
	v_fmac_f32_e32 v115, v2, v114
	v_fmac_f32_e32 v116, v3, v114
	v_fmac_f32_e32 v117, v4, v114
	v_fmac_f32_e32 v118, v5, v114
	v_fmac_f32_e32 v119, v6, v114
	v_fmac_f32_e32 v120, v7, v114
	v_fmac_f32_e32 v121, v8, v114
	v_fmac_f32_e32 v122, v9, v114
	v_fmac_f32_e32 v123, v10, v114
	v_fmac_f32_e32 v124, v11, v114
	v_fmac_f32_e32 v125, v12, v114
	v_fmac_f32_e32 v126, v13, v114
	v_fmac_f32_e32 v127, v14, v114
	v_fmac_f32_e32 v128, v15, v114
	v_fmac_f32_e32 v129, v130, v114
	ds_read2_b32 v[160:161], v0 offset0:55 offset1:56
	ds_read2_b32 v[162:163], v0 offset0:57 offset1:58
	ds_read2_b32 v[164:165], v0 offset0:59 offset1:60
	ds_read2_b32 v[166:167], v0 offset0:61 offset1:62
	ds_read2_b32 v[168:169], v0 offset0:63 offset1:64
	ds_read2_b32 v[170:171], v0 offset0:65 offset1:66
	s_waitcnt lgkmcnt(12)
	v_fmac_f32_e32 v116, v131, v115
	v_fmac_f32_e32 v117, v132, v115
	v_fmac_f32_e32 v118, v133, v115
	v_fmac_f32_e32 v119, v134, v115
	v_fmac_f32_e32 v120, v135, v115
	v_fmac_f32_e32 v121, v136, v115
	v_fmac_f32_e32 v122, v137, v115
	v_fmac_f32_e32 v123, v138, v115
	v_fmac_f32_e32 v124, v139, v115
	v_fmac_f32_e32 v125, v140, v115
	v_fmac_f32_e32 v126, v141, v115
	v_fmac_f32_e32 v127, v142, v115
	v_fmac_f32_e32 v128, v143, v115
	v_fmac_f32_e32 v129, v144, v115
	ds_read2_b32 v[172:173], v0 offset0:73 offset1:74
	ds_read2_b32 v[174:175], v0 offset0:75 offset1:76
	ds_read2_b32 v[176:177], v0 offset0:77 offset1:78
	ds_read2_b32 v[178:179], v0 offset0:79 offset1:80
	ds_read2_b32 v[180:181], v0 offset0:81 offset1:82
	ds_read2_b32 v[182:183], v0 offset0:83 offset1:91
	s_waitcnt lgkmcnt(12)
	v_fmac_f32_e32 v117, v145, v116
	v_fmac_f32_e32 v118, v146, v116
	v_fmac_f32_e32 v119, v147, v116
	v_fmac_f32_e32 v120, v148, v116
	v_fmac_f32_e32 v121, v149, v116
	v_fmac_f32_e32 v122, v150, v116
	v_fmac_f32_e32 v123, v151, v116
	v_fmac_f32_e32 v124, v152, v116
	v_fmac_f32_e32 v125, v153, v116
	v_fmac_f32_e32 v126, v156, v116
	v_fmac_f32_e32 v127, v157, v116
	v_fmac_f32_e32 v128, v158, v116
	v_fmac_f32_e32 v129, v159, v116
	ds_read2_b32 v[184:185], v0 offset0:92 offset1:93
	ds_read2_b32 v[186:187], v0 offset0:94 offset1:95
	ds_read2_b32 v[188:189], v0 offset0:96 offset1:97
	ds_read2_b32 v[190:191], v0 offset0:98 offset1:99
	ds_read2_b32 v[192:193], v0 offset0:100 offset1:109
	s_waitcnt lgkmcnt(11)
; DI bf16_t f2bf(float f) { return (bf16_t)(pack2(f, 0.f) & 0xFFFFu); }
; __device__ __forceinline__ void rwkv_chunked(unsigned char* smem, CP p, int L, int b, int h) {
;     ...
;         if (wv == 0) {
;             float u[16], cur[16], nxt[16], gcur, gnxt = 0.f;
; #pragma unroll
;             for (int i = 0; i < 16; ++i) { cur[i] = 0.f; nxt[i] = 0.f; }
;             gcur = Gs[lane * 17];
; #pragma unroll
;             for (int t = 0; t < 16; ++t) {
;                 if (t + 1 < 16) { gnxt = Gs[lane * 17 + t + 1];
; #pragma unroll
;                     for (int i = 0; i <= t; ++i) nxt[i] = Mf[i * 17 + t + 1]; }
;                 float x0 = gcur, x1 = 0.f;
; #pragma unroll
;                 for (int i = 0; i < t; ++i) { if (i & 1) x1 += u[i] * cur[i]; else x0 += u[i] * cur[i]; }
;                 u[t] = x0 + x1; UV[lane * 40 + t] = f2bf(u[t]);
; #pragma unroll
;                 for (int i = 0; i < 16; ++i) cur[i] = nxt[i];
;                 gcur = gnxt; }
;         }
	v_fmac_f32_e32 v118, v160, v117
	v_fmac_f32_e32 v119, v161, v117
	v_fmac_f32_e32 v120, v162, v117
	v_fmac_f32_e32 v121, v163, v117
	v_fmac_f32_e32 v122, v164, v117
	v_fmac_f32_e32 v123, v165, v117
	v_fmac_f32_e32 v124, v166, v117
	v_fmac_f32_e32 v125, v167, v117
	v_fmac_f32_e32 v126, v168, v117
	v_fmac_f32_e32 v127, v169, v117
	v_fmac_f32_e32 v128, v170, v117
	v_fmac_f32_e32 v129, v171, v117
	ds_read2_b32 v[2:3], v0 offset0:110 offset1:111
	ds_read2_b32 v[4:5], v0 offset0:112 offset1:113
	ds_read2_b32 v[6:7], v0 offset0:114 offset1:115
	ds_read2_b32 v[8:9], v0 offset0:116 offset1:117
	s_waitcnt lgkmcnt(9)
	v_fmac_f32_e32 v119, v172, v118
	v_fmac_f32_e32 v120, v173, v118
	v_fmac_f32_e32 v121, v174, v118
	v_fmac_f32_e32 v122, v175, v118
	v_fmac_f32_e32 v123, v176, v118
	v_fmac_f32_e32 v124, v177, v118
	v_fmac_f32_e32 v125, v178, v118
	v_fmac_f32_e32 v126, v179, v118
	v_fmac_f32_e32 v127, v180, v118
	v_fmac_f32_e32 v128, v181, v118
	v_fmac_f32_e32 v129, v182, v118
	ds_read2_b32 v[10:11], v0 offset0:127 offset1:128
	ds_read2_b32 v[12:13], v0 offset0:129 offset1:130
	ds_read2_b32 v[14:15], v0 offset0:131 offset1:132
	ds_read2_b32 v[130:131], v0 offset0:133 offset1:134
	s_waitcnt lgkmcnt(8)
	v_fmac_f32_e32 v120, v183, v119
	v_fmac_f32_e32 v121, v184, v119
	v_fmac_f32_e32 v122, v185, v119
	v_fmac_f32_e32 v123, v186, v119
	v_fmac_f32_e32 v124, v187, v119
	v_fmac_f32_e32 v125, v188, v119
	v_fmac_f32_e32 v126, v189, v119
	v_fmac_f32_e32 v127, v190, v119
	v_fmac_f32_e32 v128, v191, v119
	v_fmac_f32_e32 v129, v192, v119
	ds_read2_b32 v[132:133], v0 offset0:145 offset1:146
	ds_read2_b32 v[134:135], v0 offset0:147 offset1:148
	ds_read2_b32 v[136:137], v0 offset0:149 offset1:150
	ds_read2_b32 v[138:139], v0 offset0:151 offset1:163
	s_waitcnt lgkmcnt(8)
	v_fmac_f32_e32 v121, v193, v120
	v_fmac_f32_e32 v122, v2, v120
	v_fmac_f32_e32 v123, v3, v120
	v_fmac_f32_e32 v124, v4, v120
	v_fmac_f32_e32 v125, v5, v120
	v_fmac_f32_e32 v126, v6, v120
	v_fmac_f32_e32 v127, v7, v120
	v_fmac_f32_e32 v128, v8, v120
	v_fmac_f32_e32 v129, v9, v120
	ds_read2_b32 v[140:141], v0 offset0:164 offset1:165
	ds_read2_b32 v[142:143], v0 offset0:166 offset1:167
	ds_read2_b32 v[144:145], v0 offset0:168 offset1:181
	s_waitcnt lgkmcnt(7)
	v_fmac_f32_e32 v122, v10, v121
	v_fmac_f32_e32 v123, v11, v121
	v_fmac_f32_e32 v124, v12, v121
	v_fmac_f32_e32 v125, v13, v121
	v_fmac_f32_e32 v126, v14, v121
	v_fmac_f32_e32 v127, v15, v121
	v_fmac_f32_e32 v128, v130, v121
	v_fmac_f32_e32 v129, v131, v121
	ds_read2_b32 v[146:147], v0 offset0:182 offset1:183
	ds_read2_b32 v[148:149], v0 offset0:184 offset1:185
	s_waitcnt lgkmcnt(5)
	v_fmac_f32_e32 v123, v132, v122
	v_fmac_f32_e32 v124, v133, v122
	v_fmac_f32_e32 v125, v134, v122
	v_fmac_f32_e32 v126, v135, v122
	v_fmac_f32_e32 v127, v136, v122
	v_fmac_f32_e32 v128, v137, v122
	v_fmac_f32_e32 v129, v138, v122
	ds_read2_b32 v[150:151], v0 offset0:199 offset1:200
	ds_read2_b32 v[152:153], v0 offset0:201 offset1:202
	s_waitcnt lgkmcnt(4)
	v_fmac_f32_e32 v124, v139, v123
	v_fmac_f32_e32 v125, v140, v123
	v_fmac_f32_e32 v126, v141, v123
	v_fmac_f32_e32 v127, v142, v123
	v_fmac_f32_e32 v128, v143, v123
	v_fmac_f32_e32 v129, v144, v123
	ds_read2_b32 v[156:157], v0 offset0:217 offset1:218
	ds_read2_b32 v[158:159], v0 offset0:219 offset1:235
	s_waitcnt lgkmcnt(4)
	v_fmac_f32_e32 v125, v145, v124
	v_fmac_f32_e32 v126, v146, v124
	v_fmac_f32_e32 v127, v147, v124
	v_fmac_f32_e32 v128, v148, v124
	v_fmac_f32_e32 v129, v149, v124
	ds_read2_b32 v[160:161], v0 offset0:236 offset1:253
	s_waitcnt lgkmcnt(3)
	v_fmac_f32_e32 v126, v150, v125
	v_fmac_f32_e32 v127, v151, v125
	v_fmac_f32_e32 v128, v152, v125
	v_fmac_f32_e32 v129, v153, v125
	s_waitcnt lgkmcnt(1)
	v_fmac_f32_e32 v127, v156, v126
	v_fmac_f32_e32 v128, v157, v126
	v_fmac_f32_e32 v129, v158, v126
	s_waitcnt lgkmcnt(0)
	v_fmac_f32_e32 v128, v159, v127
	v_fmac_f32_e32 v129, v160, v127
	s_waitcnt lgkmcnt(0)
	v_fmac_f32_e32 v129, v161, v128
	v_cvt_pk_bf16_f32 v2, v114, v115
	v_cvt_pk_bf16_f32 v3, v116, v117
	v_cvt_pk_bf16_f32 v4, v118, v119
	v_cvt_pk_bf16_f32 v5, v120, v121
	v_cvt_pk_bf16_f32 v6, v122, v123
	v_cvt_pk_bf16_f32 v7, v124, v125
	v_cvt_pk_bf16_f32 v8, v126, v127
	v_cvt_pk_bf16_f32 v9, v128, v129
	ds_write_b128 v86, v[2:5] offset:18944
	ds_write_b128 v86, v[6:9] offset:18960

; DI bf16_t f2bf(float f) { return (bf16_t)(pack2(f, 0.f) & 0xFFFFu); }
; #define MFMA32(a, b, c) __builtin_amdgcn_mfma_f32_32x32x16_bf16((a), (b), (c), 0, 0, 0)
; DI int crow16(int i, int hl) { return (i & 3) + 8 * (i >> 2) + 4 * hl; }
; __device__ __forceinline__ void rwkv_chunked(unsigned char* smem, CP p, int L, int b, int h) {
;     ...
;         if (wv >= 4) { const int vb = (wv >> 1) & 1, kb = wv & 1;
; #pragma unroll
;             for (int s = 0; s < 2; ++s) zacc = MFMA32(*(const bf16x8*)(UV + (32 * vb + qi) * 40 + 16 * s + 8 * hl), *(const bf16x8*)(BKt + (32 * kb + qi) * 40 + 16 * s + 8 * hl), zacc);
;             const float pc = PC[32 * kb + qi];
; #pragma unroll
;             for (int i = 0; i < 16; ++i) { zacc[i] *= pc; ZB[(32 * vb + crow16(i, hl)) * 72 + 32 * kb + qi] = f2bf(zacc[i]); }
;         }
.LBB0_702:
	s_or_b64 exec, exec, s[16:17]
	s_and_saveexec_b64 vcc, s[52:53]
	s_cbranch_execz .LBB0_664
	ds_read_b128 v[2:5], v87 offset:18944
	ds_read_b128 v[6:9], v88 offset:13824
	ds_read_b128 v[114:117], v87 offset:18976
	ds_read_b128 v[118:121], v88 offset:13856
	ds_read_b32 v0, v89 offset:65408
	s_waitcnt lgkmcnt(3)
	v_mfma_f32_32x32x16_bf16 v[16:31], v[2:5], v[6:9], v[16:31]
	s_waitcnt lgkmcnt(1)
	v_mfma_f32_32x32x16_bf16 v[16:31], v[114:117], v[118:121], v[16:31]
	s_waitcnt lgkmcnt(0)
	s_nop 10
	v_pk_mul_f32 v[16:17], v[0:1], v[16:17] op_sel_hi:[0,1]
	v_pk_mul_f32 v[18:19], v[0:1], v[18:19] op_sel_hi:[0,1]
	v_pk_mul_f32 v[20:21], v[0:1], v[20:21] op_sel_hi:[0,1]
	v_pk_mul_f32 v[22:23], v[0:1], v[22:23] op_sel_hi:[0,1]
	v_pk_mul_f32 v[24:25], v[0:1], v[24:25] op_sel_hi:[0,1]
	v_cvt_pk_bf16_f32 v2, v16, s0
	v_cvt_pk_bf16_f32 v3, v17, s0
	v_cvt_pk_bf16_f32 v4, v18, s0
	v_cvt_pk_bf16_f32 v5, v19, s0
	v_cvt_pk_bf16_f32 v6, v20, s0
	v_cvt_pk_bf16_f32 v7, v21, s0
	v_cvt_pk_bf16_f32 v8, v22, s0
	v_cvt_pk_bf16_f32 v9, v23, s0
	ds_write_b16 v105, v2
	ds_write_b16 v105, v3 offset:144
	ds_write_b16 v105, v4 offset:288
	ds_write_b16 v105, v5 offset:432
	ds_write_b16 v105, v6 offset:1152
	ds_write_b16 v105, v7 offset:1296
	ds_write_b16 v105, v8 offset:1440
	ds_write_b16 v105, v9 offset:1584
	v_cvt_pk_bf16_f32 v2, v24, s0
	ds_write_b16 v105, v2 offset:2304
	v_cvt_pk_bf16_f32 v2, v25, s0
	v_pk_mul_f32 v[26:27], v[0:1], v[26:27] op_sel_hi:[0,1]
	ds_write_b16 v105, v2 offset:2448
	v_cvt_pk_bf16_f32 v2, v26, s0
	ds_write_b16 v105, v2 offset:2592
	v_cvt_pk_bf16_f32 v2, v27, s0
	v_pk_mul_f32 v[28:29], v[0:1], v[28:29] op_sel_hi:[0,1]
	v_pk_mul_f32 v[30:31], v[0:1], v[30:31] op_sel_hi:[0,1]
	ds_write_b16 v105, v2 offset:2736
	v_cvt_pk_bf16_f32 v2, v28, s0
	v_cvt_pk_bf16_f32 v0, v30, s0
	ds_write_b16 v105, v2 offset:3456
	v_cvt_pk_bf16_f32 v2, v29, s0
	ds_write_b16 v105, v0 offset:3744
	v_cvt_pk_bf16_f32 v0, v31, s0
	ds_write_b16 v105, v2 offset:3600
	ds_write_b16 v105, v0 offset:3888
	s_branch .LBB0_664
